# grid barrier: L1 invalidate issued by idle wave 1 right after the workgroup entry barrier (thread 0 no longer issues it)
# speedup vs baseline: 1.0040x; 1.0040x over previous
.LBB0_79:
	s_waitcnt vmcnt(0)
	s_barrier
	v_readfirstlane_b32 s98, v0
	s_cmp_eq_u32 s98, 64
	s_cbranch_scc0 .Lw1inv_0
	buffer_inv sc1
	s_waitcnt vmcnt(0)
.Lw1inv_0:
	s_mov_b64 s[0:1], exec
	v_readlane_b32 s2, v254, 2
	v_readlane_b32 s3, v254, 3
	s_and_b64 s[2:3], s[0:1], s[2:3]
	s_mov_b64 exec, s[2:3]
	s_cbranch_execz .LBB0_131
	s_add_i32 s2, 0, 0x21000
	v_mov_b32_e32 v1, s2
	s_waitcnt vmcnt(0) expcnt(0) lgkmcnt(0)
	ds_read_b32 v3, v1
	s_add_i32 s2, 0, 0x21004
	v_mov_b32_e32 v1, s2
	ds_read_b32 v1, v1
	s_waitcnt lgkmcnt(1)
	v_cmp_ne_u32_e32 vcc, 0, v3
	s_cbranch_vccnz .LBB0_95
	v_readlane_b32 s4, v254, 0
	v_readlane_b32 s5, v254, 1
	s_load_dwordx2 s[2:3], s[4:5], 0xf8
	s_load_dword s7, s[4:5], 0x100
	s_add_u32 s4, s64, 0x1000
	s_addc_u32 s5, s65, 0
	s_add_u32 s6, s64, 0x1100
	s_waitcnt lgkmcnt(0)
	s_mul_i32 s2, s3, s2
	s_mul_i32 s2, s2, s7
	s_addc_u32 s7, s65, 0
	s_add_u32 s8, s64, 0x1200
	s_addc_u32 s9, s65, 0
	s_add_u32 s10, s64, 0x1300
	s_addc_u32 s11, s65, 0
	s_mov_b32 s3, 1
	v_mov_b32_e32 v17, 0
	s_branch .LBB0_83

.Lw1inv_2:
	s_mov_b64 s[0:1], exec
	v_readlane_b32 s2, v254, 2
	v_readlane_b32 s3, v254, 3
	v_readlane_b32 s80, v254, 5
	s_and_b64 s[2:3], s[0:1], s[2:3]
	v_readlane_b32 s81, v254, 6
	s_mov_b64 exec, s[2:3]
	s_cbranch_execz .LBB0_467
	s_add_i32 s2, 0, 0x21000
	v_mov_b32_e32 v1, s2
	s_waitcnt vmcnt(0) expcnt(0) lgkmcnt(0)
	ds_read_b32 v3, v1
	s_add_i32 s2, 0, 0x21004
	v_mov_b32_e32 v1, s2
	ds_read_b32 v1, v1
	s_waitcnt lgkmcnt(1)
	v_cmp_ne_u32_e32 vcc, 0, v3
	s_cbranch_vccnz .LBB0_431
	v_readlane_b32 s4, v254, 7
	v_readlane_b32 s5, v254, 8
	s_load_dwordx2 s[2:3], s[4:5], 0x4
	s_add_u32 s4, s80, 0x1000
	s_addc_u32 s5, s81, 0
	s_add_u32 s6, s80, 0x1100
	s_addc_u32 s7, s81, 0
	s_add_u32 s8, s80, 0x1200
	s_addc_u32 s9, s81, 0
	s_waitcnt lgkmcnt(0)
	s_mul_i32 s2, s2, s84
	s_add_u32 s10, s80, 0x1300
	s_mul_i32 s2, s2, s3
	s_addc_u32 s11, s81, 0
	s_mov_b32 s3, 1
	v_mov_b32_e32 v17, 0
	s_branch .LBB0_419

.LBB0_684:
	s_waitcnt vmcnt(0)
	s_waitcnt lgkmcnt(0)
	s_barrier
	v_readfirstlane_b32 s98, v0
	s_cmp_eq_u32 s98, 64
	s_cbranch_scc0 .Lw1inv_3
	buffer_inv sc1
	s_waitcnt vmcnt(0)
.Lw1inv_3:
	s_mov_b64 s[0:1], exec
	v_readlane_b32 s2, v254, 2
	v_readlane_b32 s3, v254, 3
	s_and_b64 s[2:3], s[0:1], s[2:3]
	s_mov_b64 exec, s[2:3]
	s_cbranch_execz .LBB0_736
	s_add_i32 s2, 0, 0x21000
	v_mov_b32_e32 v1, s2
	s_waitcnt vmcnt(0) expcnt(0) lgkmcnt(0)
	ds_read_b32 v3, v1
	s_add_i32 s2, 0, 0x21004
	v_mov_b32_e32 v1, s2
	ds_read_b32 v1, v1
	s_waitcnt lgkmcnt(1)
	v_cmp_ne_u32_e32 vcc, 0, v3
	s_cbranch_vccnz .LBB0_700
	v_readlane_b32 s4, v254, 7
	v_readlane_b32 s5, v254, 8
	s_load_dwordx2 s[2:3], s[4:5], 0x4
	s_add_u32 s4, s80, 0x1000
	s_addc_u32 s5, s81, 0
	s_add_u32 s6, s80, 0x1100
	s_addc_u32 s7, s81, 0
	s_add_u32 s8, s80, 0x1200
	s_addc_u32 s9, s81, 0
	s_waitcnt lgkmcnt(0)
	s_mul_i32 s2, s2, s84
	s_add_u32 s10, s80, 0x1300
	s_mul_i32 s2, s2, s3
	s_addc_u32 s11, s81, 0
	s_mov_b32 s3, 1
	v_mov_b32_e32 v17, 0
	s_branch .LBB0_688
